# attention: bank-conflict-free LDS layouts (chunk-major ctx-K/ctx-V tiles; K/V ring with XOR+rotation swizzle so b128 reads and staging writes are conflict-free)
# speedup vs baseline: 1.0107x; 1.0107x over previous
.LBB0_101:
	s_cmp_gt_i32 s50, 7
	s_cbranch_scc0 .LBB0_162
	s_cmp_gt_i32 s50, 8
	s_mov_b64 s[0:1], -1
	s_cbranch_scc0 .LBB0_164
	s_bfe_u32 s3, s12, 0x20006
	s_cmp_lt_i32 s3, 1
	s_mov_b32 s2, s3
	s_movk_i32 s22, 0x90
	s_mov_b32 s23, 0x12000
	s_movk_i32 s24, 0x5ff
	s_mov_b32 s25, 0x80000
	s_mov_b32 s31, 0xc0000
	s_movk_i32 s34, 0x1000
	s_movk_i32 s35, 0xc0
	s_cbranch_scc1 .LBB0_108
	s_cmp_eq_u32 s3, 1
	s_cbranch_scc1 .LBB0_106
	s_cmp_eq_u32 s3, 2
	s_cselect_b32 s2, 24, 32
	s_mov_b64 s[0:1], 0

.LBB0_108:
	v_readlane_b32 s0, v252, 17
	v_readlane_b32 s1, v252, 18
	s_andn2_b64 vcc, exec, s[0:1]
	s_cbranch_vccnz .LBB0_163
	v_and_b32_e32 v63, 15, v156
	s_waitcnt vmcnt(0)
	v_mad_u32_u24 v0, v63, s22, 0
	v_and_b32_e32 v1, 48, v156
	s_movk_i32 s0, 0x180
	s_lshl_b32 s8, s3, 4
	v_add_u32_e32 v67, v0, v1
	v_mad_u32_u24 v5, v63, s0, v0
	v_lshrrev_b32_e32 v0, 4, v154
	v_lshlrev_b32_e32 v56, 3, v0
	v_or_b32_e32 v2, s8, v63
	v_add_u32_e32 v4, s2, v56
	v_med3_u32 v3, v2, 8, 56
	v_or_b32_e32 v0, 6, v4
	v_add_u32_e32 v6, -8, v3
	v_add_u32_e32 v3, 8, v3
	v_cmp_ge_u32_e32 vcc, v0, v6
	v_cmp_lt_u32_e64 s[0:1], v0, v3
	v_sub_u32_e32 v0, v0, v2
	v_lshl_add_u32 v0, v0, 16, v215
	s_and_b64 vcc, vcc, s[0:1]
	v_or_b32_e32 v7, 7, v4
	v_cndmask_b32_e32 v0, v216, v0, vcc
	v_cmp_ge_u32_e32 vcc, v7, v6
	v_cmp_lt_u32_e64 s[0:1], v7, v3
	v_sub_u32_e32 v7, v7, v2
	v_lshl_add_u32 v7, v7, 24, v217
	s_and_b64 vcc, vcc, s[0:1]
	v_or_b32_e32 v8, 5, v4
	v_cndmask_b32_e32 v7, v218, v7, vcc
	v_cmp_ge_u32_e32 vcc, v8, v6
	v_cmp_lt_u32_e64 s[0:1], v8, v3
	v_sub_u32_e32 v8, v8, v2
	v_lshl_add_u32 v8, v8, 8, v219
	s_and_b64 vcc, vcc, s[0:1]
	v_or_b32_e32 v9, 4, v4
	v_cndmask_b32_e32 v8, v220, v8, vcc
	v_cmp_ge_u32_e32 vcc, v9, v6
	v_cmp_lt_u32_e64 s[0:1], v9, v3
	v_sub_u32_e32 v9, v9, v2
	v_add_u32_e32 v9, 15, v9
	s_and_b64 vcc, vcc, s[0:1]
	v_cndmask_b32_e32 v9, 31, v9, vcc
	v_or_b32_e32 v0, v7, v0
	v_or3_b32 v7, v0, v8, v9
	v_or_b32_e32 v0, 2, v4
	v_cmp_ge_u32_e32 vcc, v0, v6
	v_cmp_lt_u32_e64 s[0:1], v0, v3
	v_sub_u32_e32 v0, v0, v2
	v_lshl_add_u32 v0, v0, 16, v215
	s_and_b64 vcc, vcc, s[0:1]
	v_or_b32_e32 v8, 3, v4
	v_cndmask_b32_e32 v0, v216, v0, vcc
	v_cmp_ge_u32_e32 vcc, v8, v6
	v_cmp_lt_u32_e64 s[0:1], v8, v3
	v_sub_u32_e32 v8, v8, v2
	v_lshl_add_u32 v8, v8, 24, v217
	s_and_b64 vcc, vcc, s[0:1]
	v_or_b32_e32 v10, 1, v4
	v_cndmask_b32_e32 v8, v218, v8, vcc
	v_cmp_ge_u32_e32 vcc, v10, v6
	v_cmp_lt_u32_e64 s[0:1], v10, v3
	v_sub_u32_e32 v10, v10, v2
	v_lshl_add_u32 v10, v10, 8, v219
	s_and_b64 vcc, vcc, s[0:1]
	v_cndmask_b32_e32 v10, v220, v10, vcc
	v_cmp_ge_u32_e32 vcc, v4, v6
	v_cmp_lt_u32_e64 s[0:1], v4, v3
	v_sub_u32_e32 v2, v4, v2
	v_add_u32_e32 v2, 15, v2
	s_and_b64 vcc, vcc, s[0:1]
	v_cndmask_b32_e32 v6, 31, v2, vcc
	v_or_b32_e32 v0, v8, v0
	v_or3_b32 v8, v0, v10, v6
	v_and_b32_e32 v10, 7, v156
	v_ashrrev_i32_e32 v79, 3, v156
	v_lshlrev_b32_e32 v0, 4, v10
	v_mad_u64_u32 v[2:3], s[0:1], v79, s22, v[0:1]
	s_movk_i32 s0, 0x2d0
	s_ashr_i32 s9, s12, 8
	v_cmp_gt_i32_e64 s[36:37], s0, v156
	s_movk_i32 s0, 0x800
	v_add_u32_e32 v78, v5, v1
	v_cmp_gt_i32_e64 s[38:39], s0, v156
	s_lshl_b32 s0, s9, 6
	v_add_u32_e32 v1, 0, v1
	s_or_b32 s10, s8, s0
	v_add_u32_e32 v82, 0x12000, v1
	v_mul_i32_i24_e32 v1, 0xfffffe80, v63
	s_mov_b32 s0, 0x14400
	v_lshlrev_b32_e32 v3, 1, v154
	v_add3_u32 v83, v5, v1, s0
	v_readlane_b32 s0, v251, 2
	v_and_b32_e32 v3, 24, v3
	v_mov_b32_e32 v57, v153
	v_readlane_b32 s1, v251, 3
	v_add_u32_e32 v3, s2, v3
	v_readlane_b32 s2, v251, 6
	v_lshl_add_u64 v[60:61], s[0:1], 0, v[56:57]
	v_readlane_b32 s0, v249, 50
	v_and_b32_e32 v152, 48, v154
	v_readlane_b32 s3, v251, 7
	s_cmp_lt_u32 s0, 4
	v_lshlrev_b32_e32 v1, 4, v156
	v_readlane_b32 s0, v251, 8
	v_lshlrev_b32_e32 v80, 1, v4
	v_and_or_b32 v3, v156, 3, v3
	v_lshlrev_b32_e32 v4, 3, v10
	v_lshl_add_u64 v[58:59], s[2:3], 0, v[152:153]
	v_and_b32_e32 v152, 0x1f0, v1
	v_readlane_b32 s1, v251, 9
	v_mov_b32_e32 v1, v153
	v_mul_u32_u24_e32 v81, 0x90, v3
	s_cselect_b64 s[40:41], -1, 0
	v_add_u32_e32 v62, 0, v0
	v_lshl_add_u64 v[64:65], s[0:1], 0, v[152:153]
	v_add_u32_e32 v66, 0, v152
	v_and_b32_e32 v84, 0xff, v6
	v_and_b32_e32 v85, 0xff, v9
	v_bfe_u32 v86, v8, 8, 8
	v_bfe_u32 v87, v7, 8, 8
	v_bfe_u32 v88, v8, 16, 8
	v_bfe_u32 v89, v7, 16, 8
	v_lshrrev_b32_e32 v90, 24, v8
	v_lshrrev_b32_e32 v91, 24, v7
	s_mov_b32 s5, 0x20200
	v_lshrrev_b32_e32 v162, 1, v80
	v_subrev_u32_e32 v162, s8, v162
	v_sub_u32_e32 v162, v162, v63
	v_add_u32_e32 v162, 15, v162
	v_sub_u32_e32 v163, 0, v162
	v_and_b32_e32 v163, 3, v163
	v_add3_u32 v162, v162, v163, 16
	v_lshlrev_b32_e32 v162, 2, v162
	v_mul_u32_u24_e32 v163, 0xf00, v163
	v_add3_u32 v162, v162, v163, s5
	v_mov_b32_e32 v163, 0xf149f2ca
	v_cmp_eq_u32_e32 vcc, 31, v84
	v_mov_b32_e32 v84, 0x42c80000
	s_nop 0
	v_cndmask_b32_e32 v84, v84, v163, vcc
	v_cmp_eq_u32_e32 vcc, 31, v85
	v_mov_b32_e32 v85, 0x42c80000
	s_nop 0
	v_cndmask_b32_e32 v85, v85, v163, vcc
	v_cmp_eq_u32_e32 vcc, 31, v86
	v_mov_b32_e32 v86, 0x42c80000
	s_nop 0
	v_cndmask_b32_e32 v86, v86, v163, vcc
	v_cmp_eq_u32_e32 vcc, 31, v87
	v_mov_b32_e32 v87, 0x42c80000
	s_nop 0
	v_cndmask_b32_e32 v87, v87, v163, vcc
	v_cmp_eq_u32_e32 vcc, 31, v88
	v_mov_b32_e32 v88, 0x42c80000
	s_nop 0
	v_cndmask_b32_e32 v88, v88, v163, vcc
	v_cmp_eq_u32_e32 vcc, 31, v89
	v_mov_b32_e32 v89, 0x42c80000
	s_nop 0
	v_cndmask_b32_e32 v89, v89, v163, vcc
	v_cmp_eq_u32_e32 vcc, 31, v90
	v_mov_b32_e32 v90, 0x42c80000
	s_nop 0
	v_cndmask_b32_e32 v90, v90, v163, vcc
	v_cmp_eq_u32_e32 vcc, 31, v91
	v_mov_b32_e32 v91, 0x42c80000
	s_nop 0
	v_cndmask_b32_e32 v91, v91, v163, vcc
	v_lshl_add_u64 v[68:69], s[2:3], 0, v[0:1]
	v_lshlrev_b32_e32 v152, 1, v4
	v_add_u32_e32 v92, 0, v2
	v_lshrrev_b32_e32 v0, 3, v56
	v_lshlrev_b32_e32 v1, 8, v0
	v_lshl_add_u32 v67, v63, 4, v1
	v_mov_b32_e32 v78, v67
	v_lshrrev_b32_e32 v2, 1, v80
	v_sub_u32_e32 v2, v2, v56
	v_lshrrev_b32_e32 v5, 3, v2
	v_lshrrev_b32_e32 v3, 2, v63
	v_and_b32_e32 v4, 3, v63
	v_add_u32_e32 v6, v5, v3
	v_and_b32_e32 v7, 1, v0
	v_xor_b32_e32 v4, v4, v7
	v_lshrrev_b32_e32 v7, 1, v0
	v_add_u32_e32 v8, v6, v7
	v_and_b32_e32 v9, 3, v8
	v_add_u32_e32 v8, 2, v8
	v_and_b32_e32 v8, 3, v8
	v_lshrrev_b32_e32 v6, 2, v6
	v_and_b32_e32 v6, 1, v6
	v_lshl_or_b32 v9, v9, 2, v4
	v_lshl_or_b32 v9, v6, 5, v9
	v_lshl_or_b32 v8, v8, 2, v4
	v_lshl_or_b32 v8, v6, 5, v8
	v_lshlrev_b32_e32 v10, 10, v0
	v_lshl_add_u32 v9, v9, 4, v10
	v_add_u32_e32 v81, 0x12000, v9
	v_lshl_add_u32 v8, v8, 4, v10
	v_add_u32_e32 v82, 0x13000, v8
	v_add_u32_e32 v11, v5, v0
	v_and_b32_e32 v12, 1, v11
	v_mul_u32_u24_e32 v12, 12, v12
	v_bfe_u32 v13, v11, 1, 2
	v_xor_b32_e32 v12, v12, v13
	v_xor_b32_e32 v12, v12, v63
	v_lshlrev_b32_e32 v12, 4, v12
	v_lshl_add_u32 v12, v11, 10, v12
	v_add_u32_e32 v83, 0x14000, v12
	v_lshrrev_b32_e32 v14, 3, v156
	v_and_b32_e32 v15, 7, v156
	v_and_b32_e32 v16, 1, v15
	v_lshrrev_b32_e32 v17, 1, v15
	v_and_b32_e32 v18, 3, v14
	v_xor_b32_e32 v18, v18, v16
	v_bfe_u32 v19, v14, 3, 2
	v_add_u32_e32 v19, v19, v17
	v_and_b32_e32 v19, 3, v19
	v_lshl_or_b32 v18, v19, 2, v18
	v_bfe_u32 v19, v14, 2, 1
	v_lshl_or_b32 v18, v19, 4, v18
	v_bfe_u32 v19, v14, 5, 1
	v_lshl_or_b32 v18, v19, 5, v18
	v_lshlrev_b32_e32 v20, 10, v15
	v_lshl_add_u32 v92, v18, 4, v20
	v_mul_u32_u24_e32 v18, 12, v16
	v_xor_b32_e32 v18, v18, v17
	v_and_b32_e32 v19, 15, v14
	v_xor_b32_e32 v18, v18, v19
	v_lshrrev_b32_e32 v19, 4, v14
	v_lshlrev_b32_e32 v18, 4, v18
	v_lshl_add_u32 v18, v19, 8, v18
	v_add_u32_e32 v235, v18, v20
	s_mov_b32 s11, s28
	s_mov_b32 s12, s28
	s_branch .LBB0_111

.LBB0_111:
	s_barrier
	s_lshl_b32 s0, s12, 6
	s_ashr_i32 s14, s12, 4
	s_and_b32 s13, s0, 0x3c0
	s_mov_b32 s5, 0x20200
	s_and_b32 s4, s11, 15
	s_mulk_i32 s4, 0x1d1
	v_and_b32_e32 v0, 63, v156
	v_bfe_u32 v1, v156, 6, 2
	v_lshrrev_b32_e32 v2, 8, v156
	v_sub_u32_e32 v3, v0, v1
	v_add_u32_e32 v3, -16, v3
	v_med3_i32 v4, v3, 0, 30
	v_lshlrev_b32_e32 v5, 3, v2
	v_mad_u32_u24 v6, v5, 31, v4
	v_add_lshl_u32 v6, v6, s4, 2
	v_lshlrev_b32_e32 v7, 2, v0
	v_mul_u32_u24_e32 v16, 0xf00, v1
	v_lshl_add_u32 v7, v5, 8, v7
	v_add3_u32 v7, v7, v16, s5
	v_cmp_eq_u32_e32 vcc, 0, v2
	v_add_u32_e32 v17, 0x2e8, v6
	v_add_u32_e32 v18, 0x364, v6
	v_lshl_add_u32 v19, v1, 8, 0
	v_cndmask_b32_e32 v17, v17, v18, vcc
	v_lshl_add_u32 v19, v0, 2, v19
	v_add_u32_e32 v18, 0x700, v7
	v_cndmask_b32_e32 v19, v19, v18, vcc
	global_load_dword v8, v6, s[64:65] offset:0
	global_load_dword v9, v6, s[64:65] offset:124
	global_load_dword v10, v6, s[64:65] offset:248
	global_load_dword v11, v6, s[64:65] offset:372
	global_load_dword v12, v6, s[64:65] offset:496
	global_load_dword v13, v6, s[64:65] offset:620
	global_load_dword v14, v6, s[64:65] offset:744
	global_load_dword v15, v17, s[64:65]
	s_lshl_b32 s2, s14, 8
	s_lshl_b32 s26, s13, 1
	s_add_i32 s2, s2, 0x8000
	v_lshl_add_u64 v[16:17], v[68:69], 0, s[26:27]
	v_ashrrev_i32_e32 v18, 3, v156
	v_add_u32_e32 v20, s2, v18
	v_ashrrev_i32_e32 v21, 31, v20
	v_lshlrev_b64 v[20:21], 12, v[20:21]
	v_lshl_add_u64 v[20:21], v[16:17], 0, v[20:21]
	s_mov_b32 s16, 0x40000
	global_load_dwordx4 v[24:27], v[20:21], off offset:2048
	v_add_co_u32_e32 v20, vcc, s16, v20
	s_nop 1
	v_addc_co_u32_e32 v21, vcc, 0, v21, vcc
	global_load_dwordx4 v[28:31], v[20:21], off offset:2048
	v_add_co_u32_e32 v20, vcc, s16, v20
	s_nop 1
	v_addc_co_u32_e32 v21, vcc, 0, v21, vcc
	global_load_dwordx4 v[32:35], v[20:21], off offset:2048
	v_add_co_u32_e32 v20, vcc, s16, v20
	s_nop 1
	v_addc_co_u32_e32 v21, vcc, 0, v21, vcc
	global_load_dwordx4 v[36:39], v[20:21], off offset:2048
	v_lshlrev_b32_e32 v22, 2, v18
	v_lshrrev_b32_e32 v23, 1, v18
	v_and_b32_e32 v1, 0xfffffe3, v18
	v_and_b32_e32 v22, 16, v22
	v_and_b32_e32 v23, 12, v23
	v_or3_b32 v1, v1, v22, v23
	v_lshrrev_b32_e32 v22, 4, v1
	v_and_b32_e32 v23, 15, v1
	v_lshlrev_b32_e32 v22, 11, v22
	v_lshl_add_u32 v22, v23, 4, v22
	v_lshl_add_u32 v1, v62, 4, v22
	s_ashr_i32 s3, s2, 31
	v_lshl_add_u64 v[16:17], s[2:3], 1, v[64:65]
	v_ashrrev_i32_e32 v18, 5, v156
	v_add_u32_e32 v20, s13, v18
	v_mad_i64_i32 v[20:21], s[16:17], v20, s23, v[16:17]
	s_mov_b32 s4, 0x120000
	global_load_dwordx4 v[40:43], v[20:21], off
	v_add_co_u32_e32 v20, vcc, s4, v20
	s_nop 1
	v_addc_co_u32_e32 v21, vcc, 0, v21, vcc
	global_load_dwordx4 v[44:47], v[20:21], off
	v_add_co_u32_e32 v20, vcc, s4, v20
	s_nop 1
	v_addc_co_u32_e32 v21, vcc, 0, v21, vcc
	global_load_dwordx4 v[48:51], v[20:21], off
	v_add_co_u32_e32 v20, vcc, s4, v20
	s_nop 1
	v_addc_co_u32_e32 v21, vcc, 0, v21, vcc
	global_load_dwordx4 v[52:55], v[20:21], off
	v_bfe_u32 v22, v66, 4, 2
	v_lshlrev_b32_e32 v22, 8, v22
	v_lshrrev_b32_e32 v16, 6, v66
	v_lshl_add_u32 v22, v16, 12, v22
	v_lshl_add_u32 v23, v18, 4, v22
	v_cmp_gt_u32_e64 s[2:3], 31, v3
	s_waitcnt vmcnt(8)
	v_mul_f32_e32 v8, 0x3fb8aa3b, v8
	v_cndmask_b32_e64 v8, 0, v8, s[2:3]
	v_mul_f32_e32 v9, 0x3fb8aa3b, v9
	v_cndmask_b32_e64 v9, 0, v9, s[2:3]
	v_mul_f32_e32 v10, 0x3fb8aa3b, v10
	v_cndmask_b32_e64 v10, 0, v10, s[2:3]
	v_mul_f32_e32 v11, 0x3fb8aa3b, v11
	v_cndmask_b32_e64 v11, 0, v11, s[2:3]
	v_mul_f32_e32 v12, 0x3fb8aa3b, v12
	v_cndmask_b32_e64 v12, 0, v12, s[2:3]
	v_mul_f32_e32 v13, 0x3fb8aa3b, v13
	v_cndmask_b32_e64 v13, 0, v13, s[2:3]
	v_mul_f32_e32 v14, 0x3fb8aa3b, v14
	v_cndmask_b32_e64 v14, 0, v14, s[2:3]
	v_mul_f32_e32 v15, 0x3fb8aa3b, v15
	v_cndmask_b32_e64 v15, 0, v15, s[2:3]
	ds_write_b32 v7, v8 offset:0
	ds_write_b32 v7, v9 offset:256
	ds_write_b32 v7, v10 offset:512
	ds_write_b32 v7, v11 offset:768
	ds_write_b32 v7, v12 offset:1024
	ds_write_b32 v7, v13 offset:1280
	ds_write_b32 v7, v14 offset:1536
	ds_write_b32 v19, v15
	s_waitcnt vmcnt(7)
	ds_write_b128 v1, v[24:27] offset:3072
	s_waitcnt vmcnt(6)
	ds_write_b128 v1, v[28:31] offset:11264
	s_waitcnt vmcnt(5)
	ds_write_b128 v1, v[32:35] offset:19456
	s_waitcnt vmcnt(4)
	ds_write_b128 v1, v[36:39] offset:27648
	s_waitcnt vmcnt(3)
	ds_write_b128 v23, v[40:43] offset:39936
	s_waitcnt vmcnt(2)
	ds_write_b128 v23, v[44:47] offset:40960
	s_waitcnt vmcnt(1)
	ds_write_b128 v23, v[48:51] offset:41984
	s_waitcnt vmcnt(0)
	ds_write_b128 v23, v[52:55] offset:43008
.LBB0_121:
	s_lshl_b32 s0, s14, 11
	s_waitcnt vmcnt(0)
	v_add_u32_e32 v0, s0, v79
	v_ashrrev_i32_e32 v1, 31, v0
	v_readlane_b32 s4, v251, 6
	v_lshlrev_b64 v[0:1], 12, v[0:1]
	v_readlane_b32 s5, v251, 7
	s_lshl_b32 s26, s13, 1
	v_readlane_b32 s2, v251, 8
	v_lshl_add_u64 v[0:1], s[4:5], 0, v[0:1]
	v_lshl_add_u64 v[0:1], v[0:1], 0, s[26:27]
	v_readlane_b32 s3, v251, 9
	v_lshl_add_u64 v[70:71], v[0:1], 0, v[152:153]
	v_add_u32_e32 v2, s13, v79
	v_mov_b64_e32 v[0:1], s[2:3]
	v_mad_i64_i32 v[0:1], s[2:3], v2, s23, v[0:1]
	s_ashr_i32 s1, s0, 31
	v_lshl_add_u64 v[0:1], s[0:1], 1, v[0:1]
	v_lshl_add_u64 v[72:73], v[0:1], 0, v[152:153]
	global_load_dwordx4 v[0:3], v[70:71], off offset:2048
	global_load_dwordx4 v[4:7], v[72:73], off
	global_load_dwordx4 v[8:11], v[72:73], off offset:128
	s_mov_b32 s1, 0x40000
	v_add_co_u32_e32 v12, vcc, s1, v70
	s_add_i32 s2, s10, s0
	s_nop 0
	v_addc_co_u32_e32 v13, vcc, 0, v71, vcc
	global_load_dwordx4 v[12:15], v[12:13], off offset:2048
	v_or_b32_e32 v20, s2, v63
	v_ashrrev_i32_e32 v21, 31, v20
	v_add_co_u32_e32 v24, vcc, s25, v70
	v_lshlrev_b64 v[20:21], 12, v[20:21]
	s_nop 0
	v_addc_co_u32_e32 v25, vcc, 0, v71, vcc
	v_lshl_add_u64 v[20:21], s[4:5], 0, v[20:21]
	v_add_co_u32_e32 v26, vcc, s31, v70
	v_add_u32_e32 v96, 0x18800, v235
	v_lshl_add_u64 v[20:21], v[20:21], 0, s[26:27]
	v_addc_co_u32_e32 v27, vcc, 0, v71, vcc
	v_add_u32_e32 v93, 0x12000, v92
	v_add_u32_e32 v94, 0x14000, v235
	v_add_u32_e32 v95, 0x16800, v92
	global_load_dwordx4 v[16:19], v[72:73], off offset:256
	v_lshl_add_u64 v[32:33], v[56:57], 1, v[20:21]
	global_load_dwordx4 v[20:23], v[72:73], off offset:384
	global_load_dwordx4 v[28:31], v[24:25], off offset:2048
	s_nop 0
	global_load_dwordx4 v[24:27], v[26:27], off offset:2048
	v_mov_b32_e32 v100, 0
	s_mov_b32 s1, 0
	s_or_b32 s0, s0, s8
	v_lshl_add_u64 v[74:75], v[58:59], 0, s[26:27]
	v_lshl_add_u64 v[76:77], v[60:61], 0, s[26:27]
	v_mov_b32_e32 v101, 0xf149f2ca
	s_mov_b32 s15, 4
	s_mov_b32 s5, 8
	s_mov_b32 s3, -3
	v_mov_b32_e32 v97, 0
	v_mov_b32_e32 v98, 8
	v_mov_b32_e32 v99, 0
	s_mov_b32 s14, 0
	s_mov_b32 s13, s9
	s_mov_b32 s4, 0
	s_mov_b32 s16, 4
	v_mov_b32_e32 v34, v100
	v_mov_b32_e32 v35, v100
	v_mov_b32_e32 v36, v100
	v_mov_b32_e32 v37, v100
	v_mov_b32_e32 v38, v100
	v_mov_b32_e32 v39, v100
	v_mov_b32_e32 v40, v100
	v_mov_b32_e32 v41, v100
	v_mov_b32_e32 v42, v100
	v_mov_b32_e32 v43, v100
	v_mov_b32_e32 v44, v100
	v_mov_b32_e32 v45, v100
	v_mov_b32_e32 v46, v100
	v_mov_b32_e32 v47, v100
	s_waitcnt vmcnt(0)
	ds_write_b128 v96, v[8:11]
	ds_write_b128 v94, v[4:7]
	ds_write_b128 v93, v[0:3]
	s_waitcnt vmcnt(4)
	ds_write_b128 v95, v[12:15]
	s_waitcnt lgkmcnt(0)
	s_barrier
	global_load_dwordx4 v[0:3], v[32:33], off
	global_load_dwordx4 v[4:7], v[32:33], off offset:64
	v_mov_b32_e32 v8, v153
	v_mov_b32_e32 v9, v153
	v_mov_b32_e32 v10, v153
	v_mov_b32_e32 v11, v153
	v_mov_b32_e32 v12, v153
	v_mov_b32_e32 v13, v153
	v_mov_b32_e32 v14, v153
	v_mov_b32_e32 v15, v153
	v_mov_b32_e32 v32, 0
	v_mov_b32_e32 v33, v100
	v_add_u32_e32 v226, 0x1b000, v92
	v_add_u32_e32 v227, 0x1d000, v235
	v_mov_b32_e32 v144, 0x3f803f80
	v_mov_b32_e32 v145, v144
	v_mov_b32_e32 v146, v144
	v_mov_b32_e32 v147, v144
	v_sub_u32_e32 v102, v97, v99
	v_add_u32_e32 v102, s14, v102
	v_cmp_gt_u32_e32 vcc, 8, v102
	s_cbranch_vccz .Lpf_skip_init
	v_mad_u32_u24 v103, v102, s34, v67
	v_subrev_u32_e32 v120, s13, v99
	ds_read_b128 v[166:169], v103 offset:3072
	ds_read_b128 v[174:177], v103 offset:5120
	ds_read_b128 v[170:173], v103 offset:4096
	ds_read_b128 v[178:181], v103 offset:6144
	v_add3_u32 v120, v120, v102, 7
	ds_read_b128 v[182:185], v81 offset:0
	ds_read_b128 v[190:193], v81 offset:256
	ds_read_b128 v[186:189], v82 offset:0
	ds_read_b128 v[194:197], v82 offset:256
	v_lshl_add_u32 v120, v120, 8, v162
	ds_read_b128 v[112:115], v120
	ds_read_b128 v[116:119], v120 offset:16
	s_waitcnt lgkmcnt(10)
	s_branch .Lpf_done_init

.LBB0_122:
	s_waitcnt vmcnt(4)
	ds_write_b128 v95, v[48:51]
	ds_write_b128 v96, v[52:55]
	v_sub_u32_e32 v102, v97, v99
	v_add_u32_e32 v102, s14, v102
	v_cmp_gt_u32_e32 vcc, 8, v102
	s_cbranch_vccz .Lpf_skip_a
	v_mad_u32_u24 v103, v102, s34, v67
	v_subrev_u32_e32 v120, s13, v99
	ds_read_b128 v[166:169], v103 offset:3072
	ds_read_b128 v[174:177], v103 offset:5120
	ds_read_b128 v[170:173], v103 offset:4096
	ds_read_b128 v[178:181], v103 offset:6144
	v_add3_u32 v120, v120, v102, 7
	ds_read_b128 v[182:185], v81 offset:0
	ds_read_b128 v[190:193], v81 offset:256
	ds_read_b128 v[186:189], v82 offset:0
	ds_read_b128 v[194:197], v82 offset:256
	v_lshl_add_u32 v120, v120, 8, v162
	ds_read_b128 v[112:115], v120
	ds_read_b128 v[116:119], v120 offset:16
	s_waitcnt lgkmcnt(10)
	s_branch .Lpf_done_a

.LBB0_133:
	s_cmp_lt_i32 s4, 16
	s_cselect_b32 s18, s15, 0
	s_ashr_i32 s19, s18, 31
	s_lshl_b64 s[20:21], s[18:19], 18
	s_lshl_b32 s18, s18, 6
	s_ashr_i32 s19, s18, 31
	s_waitcnt vmcnt(4)
	ds_write_b128 v226, v[28:31]
	ds_write_b128 v227, v[16:19]
	v_sub_u32_e32 v102, v97, v99
	v_add_u32_e32 v102, s14, v102
	v_cmp_gt_u32_e32 vcc, 8, v102
	s_cbranch_vccz .Lpf_skip_b
	v_mad_u32_u24 v103, v102, s34, v67
	v_subrev_u32_e32 v120, s13, v99
	ds_read_b128 v[166:169], v103 offset:3072
	ds_read_b128 v[174:177], v103 offset:5120
	ds_read_b128 v[170:173], v103 offset:4096
	ds_read_b128 v[178:181], v103 offset:6144
	v_add3_u32 v120, v120, v102, 7
	ds_read_b128 v[182:185], v81 offset:18432
	ds_read_b128 v[190:193], v81 offset:18688
	ds_read_b128 v[186:189], v82 offset:18432
	ds_read_b128 v[194:197], v82 offset:18688
	v_lshl_add_u32 v120, v120, 8, v162
	ds_read_b128 v[112:115], v120
	ds_read_b128 v[116:119], v120 offset:16
	s_waitcnt lgkmcnt(10)
	s_branch .Lpf_done_b

.LBB0_143:
	s_cmp_lt_i32 s4, 16
	s_cselect_b32 s18, s16, 0
	s_ashr_i32 s19, s18, 31
	s_lshl_b64 s[20:21], s[18:19], 18
	s_lshl_b32 s18, s18, 6
	s_ashr_i32 s19, s18, 31
	s_waitcnt vmcnt(4)
	ds_write_b128 v93, v[24:27]
	ds_write_b128 v94, v[20:23]
	v_sub_u32_e32 v102, v97, v99
	v_add_u32_e32 v102, s14, v102
	v_cmp_gt_u32_e32 vcc, 8, v102
	s_cbranch_vccz .Lpf_skip_c
	v_mad_u32_u24 v103, v102, s34, v67
	v_subrev_u32_e32 v120, s13, v99
	ds_read_b128 v[166:169], v103 offset:3072
	ds_read_b128 v[174:177], v103 offset:5120
	ds_read_b128 v[170:173], v103 offset:4096
	ds_read_b128 v[178:181], v103 offset:6144
	v_add3_u32 v120, v120, v102, 7
	ds_read_b128 v[182:185], v81 offset:36864
	ds_read_b128 v[190:193], v81 offset:37120
	ds_read_b128 v[186:189], v82 offset:36864
	ds_read_b128 v[194:197], v82 offset:37120
	v_lshl_add_u32 v120, v120, 8, v162
	ds_read_b128 v[112:115], v120
	ds_read_b128 v[116:119], v120 offset:16
	s_waitcnt lgkmcnt(10)
	s_branch .Lpf_done_c

.LBB0_152:
	v_lshl_add_u32 v137, v102, 12, v78
	ds_read_b128 v[198:201], v137 offset:39936
	ds_read_b128 v[202:205], v137 offset:40960
	ds_read_b128 v[206:209], v137 offset:41984
	ds_read_b128 v[232:235], v137 offset:43008
	s_waitcnt lgkmcnt(4)
	v_mfma_f32_16x16x32_bf16 v[104:107], v[166:169], v[8:11], v[140:143]
	v_add_f32_e32 v112, v112, v148
	v_add_f32_e32 v113, v113, v149
	v_mfma_f32_16x16x32_bf16 v[108:111], v[174:177], v[8:11], v[140:143]
	v_add_f32_e32 v114, v114, v150
	v_add_f32_e32 v115, v115, v151
	v_mfma_f32_16x16x32_bf16 v[104:107], v[170:173], v[12:15], v[104:107]
	v_add_f32_e32 v116, v116, v158
	v_add_f32_e32 v117, v117, v159
	v_mfma_f32_16x16x32_bf16 v[108:111], v[178:181], v[12:15], v[108:111]
	v_add_f32_e32 v118, v118, v160
	v_add_f32_e32 v119, v119, v161
	ds_read_b128 v[236:239], v83 offset:0
	ds_read_b128 v[240:243], v83 offset:256
	ds_read_b128 v[244:247], v83 offset:512
	ds_read_b128 v[228:231], v83 offset:768
	v_mfma_f32_16x16x32_bf16 v[112:115], v[182:185], v[8:11], v[112:115]
	v_mfma_f32_16x16x32_bf16 v[116:119], v[190:193], v[8:11], v[116:119]
	v_mfma_f32_16x16x32_bf16 v[112:115], v[186:189], v[12:15], v[112:115]
	v_mfma_f32_16x16x32_bf16 v[116:119], v[194:197], v[12:15], v[116:119]
	v_max3_f32 v121, v104, v105, v106
	v_max3_f32 v122, v108, v109, v110
	v_max3_f32 v121, v121, v107, v111
	s_nop 3
	v_max3_f32 v123, v112, v113, v114
	v_max3_f32 v122, v122, v116, v117
	v_max3_f32 v121, v121, v115, v118
	v_max3_f32 v121, v121, v122, v123
	v_max_f32_e32 v121, v121, v119
	v_cmp_lt_f32_e32 vcc, 0x41000000, v121
	s_cbranch_vccnz .Lrare_a

.LBB0_154:
	v_lshl_add_u32 v137, v102, 12, v78
	ds_read_b128 v[198:201], v137 offset:39936
	ds_read_b128 v[202:205], v137 offset:40960
	ds_read_b128 v[206:209], v137 offset:41984
	ds_read_b128 v[232:235], v137 offset:43008
	s_waitcnt lgkmcnt(4)
	v_mfma_f32_16x16x32_bf16 v[104:107], v[166:169], v[8:11], v[140:143]
	v_add_f32_e32 v112, v112, v148
	v_add_f32_e32 v113, v113, v149
	v_mfma_f32_16x16x32_bf16 v[108:111], v[174:177], v[8:11], v[140:143]
	v_add_f32_e32 v114, v114, v150
	v_add_f32_e32 v115, v115, v151
	v_mfma_f32_16x16x32_bf16 v[104:107], v[170:173], v[12:15], v[104:107]
	v_add_f32_e32 v116, v116, v158
	v_add_f32_e32 v117, v117, v159
	v_mfma_f32_16x16x32_bf16 v[108:111], v[178:181], v[12:15], v[108:111]
	v_add_f32_e32 v118, v118, v160
	v_add_f32_e32 v119, v119, v161
	ds_read_b128 v[236:239], v83 offset:18432
	ds_read_b128 v[240:243], v83 offset:18688
	ds_read_b128 v[244:247], v83 offset:18944
	ds_read_b128 v[228:231], v83 offset:19200
	v_mfma_f32_16x16x32_bf16 v[112:115], v[182:185], v[8:11], v[112:115]
	v_mfma_f32_16x16x32_bf16 v[116:119], v[190:193], v[8:11], v[116:119]
	v_mfma_f32_16x16x32_bf16 v[112:115], v[186:189], v[12:15], v[112:115]
	v_mfma_f32_16x16x32_bf16 v[116:119], v[194:197], v[12:15], v[116:119]
	v_max3_f32 v121, v104, v105, v106
	v_max3_f32 v122, v108, v109, v110
	v_max3_f32 v121, v121, v107, v111
	s_nop 3
	v_max3_f32 v123, v112, v113, v114
	v_max3_f32 v122, v122, v116, v117
	v_max3_f32 v121, v121, v115, v118
	v_max3_f32 v121, v121, v122, v123
	v_max_f32_e32 v121, v121, v119
	v_cmp_lt_f32_e32 vcc, 0x41000000, v121
	s_cbranch_vccnz .Lrare_b

.LBB0_156:
	v_lshl_add_u32 v137, v102, 12, v78
	ds_read_b128 v[198:201], v137 offset:39936
	ds_read_b128 v[202:205], v137 offset:40960
	ds_read_b128 v[206:209], v137 offset:41984
	ds_read_b128 v[232:235], v137 offset:43008
	s_waitcnt lgkmcnt(4)
	v_mfma_f32_16x16x32_bf16 v[104:107], v[166:169], v[8:11], v[140:143]
	v_add_f32_e32 v112, v112, v148
	v_add_f32_e32 v113, v113, v149
	v_mfma_f32_16x16x32_bf16 v[108:111], v[174:177], v[8:11], v[140:143]
	v_add_f32_e32 v114, v114, v150
	v_add_f32_e32 v115, v115, v151
	v_mfma_f32_16x16x32_bf16 v[104:107], v[170:173], v[12:15], v[104:107]
	v_add_f32_e32 v116, v116, v158
	v_add_f32_e32 v117, v117, v159
	v_mfma_f32_16x16x32_bf16 v[108:111], v[178:181], v[12:15], v[108:111]
	v_add_f32_e32 v118, v118, v160
	v_add_f32_e32 v119, v119, v161
	ds_read_b128 v[236:239], v83 offset:36864
	ds_read_b128 v[240:243], v83 offset:37120
	ds_read_b128 v[244:247], v83 offset:37376
	ds_read_b128 v[228:231], v83 offset:37632
	v_mfma_f32_16x16x32_bf16 v[112:115], v[182:185], v[8:11], v[112:115]
	v_mfma_f32_16x16x32_bf16 v[116:119], v[190:193], v[8:11], v[116:119]
	v_mfma_f32_16x16x32_bf16 v[112:115], v[186:189], v[12:15], v[112:115]
	v_mfma_f32_16x16x32_bf16 v[116:119], v[194:197], v[12:15], v[116:119]
	v_max3_f32 v121, v104, v105, v106
	v_max3_f32 v122, v108, v109, v110
	v_max3_f32 v121, v121, v107, v111
	s_nop 3
	v_max3_f32 v123, v112, v113, v114
	v_max3_f32 v122, v122, v116, v117
	v_max3_f32 v121, v121, v115, v118
	v_max3_f32 v121, v121, v122, v123
	v_max_f32_e32 v121, v121, v119
	v_cmp_lt_f32_e32 vcc, 0x41000000, v121
	s_cbranch_vccnz .Lrare_c
